# FFN-up GEMM k-loop: MFMA pairs that the compiler chained through a temporary register (k=1 MFMA reading the k=0 result right behind it) rewritten in place in the regular order
# baseline (speedup 1.0000x reference)
; #define PG8_STAGE(bufoff, gbase, voff) do { _Pragma("unroll") for (int _i = 0; _i < 2; ++_i) \
;         __builtin_amdgcn_global_load_lds((const unsigned*)((const char*)(gbase) + (voff)[_i]), (LAS unsigned*)(lds + (bufoff) + ldsw + _i * 8192), 16, 0, 0); } while (0)
; #define PG8_LDA(dst, b, h) do { _Pragma("unroll") for (int m = 0; m < 4; ++m) _Pragma("unroll") for (int k = 0; k < 2; ++k) dst[m][k] = *(const LAS bf16x8*)(lds + PG8_SA(b, h) + aoff + m * 2048 + k * 1024); } while (0)
; #define PG8_LDB(dst, b, h) do { _Pragma("unroll") for (int n = 0; n < 2; ++n) _Pragma("unroll") for (int k = 0; k < 2; ++k) dst[n][k] = *(const LAS bf16x8*)(lds + PG8_SB(b, h) + boff + n * 2048 + k * 1024); } while (0)
; #define PG8_MMA(ai, bj, At, Bt) do { __builtin_amdgcn_s_setprio(1); _Pragma("unroll") for (int m = 0; m < 4; ++m) _Pragma("unroll") for (int n = 0; n < 2; ++n) _Pragma("unroll") for (int k = 0; k < 2; ++k) \
;         acc[ai][bj][m][n] = __builtin_amdgcn_mfma_f32_16x16x32_bf16(Bt[n][k], At[m][k], acc[ai][bj][m][n], 0, 0, 0); __builtin_amdgcn_s_setprio(0); } while (0)
; #define PG8_WAIT_V(n) asm volatile("s_waitcnt vmcnt(" #n ")" ::: "memory")
; #define PG8_WAIT_L(n) asm volatile("s_waitcnt lgkmcnt(" #n ")" ::: "memory")
; template <class Epi>
; __device__ __forceinline__ void gemm_phase(const int tid, LAS unsigned char* lds, const Gemm g, const StaticOrder& S, const Epi& E) {
;     ...
;             const bool last = (t == nt - 2);
;             const char* a1 = cA + (size_t)(t + 1) * kstep;
;             const char* a2 = last ? nA : cA + (size_t)(t + 2) * kstep; const char* b2 = last ? nB : cB + (size_t)(t + 2) * kstep;
;             const char* a3 = a2 + kstep; const char* b3 = b2 + kstep;
;             if constexpr (Epi::HOOK) { if (t == 16 || t == 32) { PG8_SCHED; E.hook(acc, cur, t == 16 ? 0 : 1, wr, wc, fr, fq); PG8_SCHED; } }
;             PG8_LDB(B0, 0, 0); PG8_LDB(B1, 0, 1); PG8_SCHED; PG8_LDA(At, 0, 0); PG8_STAGE(PG8_SA(1, 1), a1 + hstepA, voffA);
;             PG8_WAIT_V(8); PG8_WAIT_L(0); PG8_BAR; PG8_MMA(0, 0, At, B0); PG8_MMA(0, 1, At, B1); PG8_BAR; PG8_SCHED;
;             PG8_LDA(At, 0, 1); PG8_STAGE(PG8_SB(0, 0), b2, voffB); PG8_STAGE(PG8_SB(0, 1), b2 + hstepB, voffB); PG8_STAGE(PG8_SA(0, 0), a2, voffA);
;             PG8_WAIT_V(8); PG8_WAIT_L(0); PG8_BAR; PG8_MMA(1, 0, At, B0); PG8_MMA(1, 1, At, B1); PG8_BAR; PG8_SCHED;
.LBB0_5496:
	s_add_u32 s28, s0, 0xfff80080
	s_addc_u32 s29, s1, -1
	s_add_i32 s53, 0, 0x10000
	s_cmp_eq_u32 s52, 28
	s_cselect_b32 s51, s5, s29
	s_cselect_b32 s50, s19, s28
	s_cselect_b32 s29, s34, s45
	s_cselect_b32 s28, s35, s43
	s_add_i32 s56, 0, 0x14000
	v_add_u32_e32 v62, s53, v33
	v_add_u32_e32 v86, s56, v33
	ds_read_b128 v[50:53], v62
	ds_read_b128 v[54:57], v62 offset:1024
	ds_read_b128 v[58:61], v62 offset:2048
	ds_read_b128 v[62:65], v62 offset:3072
	ds_read_b128 v[70:73], v86
	ds_read_b128 v[78:81], v86 offset:1024
	ds_read_b128 v[82:85], v86 offset:2048
	ds_read_b128 v[86:89], v86 offset:3072
	v_lshl_add_u64 v[198:199], s[0:1], 0, v[170:171]
	s_add_i32 m0, s60, 0xc000
	ds_read_b128 v[174:177], v200
	ds_read_b128 v[178:181], v200 offset:1024
	ds_read_b128 v[182:185], v200 offset:2048
	ds_read_b128 v[186:189], v200 offset:3072
	ds_read_b128 v[190:193], v200 offset:4096
	ds_read_b128 v[194:197], v200 offset:5120
	ds_read_b128 v[202:205], v200 offset:6144
	ds_read_b128 v[206:209], v200 offset:7168
	global_load_lds_dwordx4 v[198:199], off
	v_lshl_add_u64 v[198:199], s[0:1], 0, v[172:173]
	s_add_i32 m0, s60, 0xe000
	s_nop 0
	global_load_lds_dwordx4 v[198:199], off
	s_waitcnt vmcnt(8)
	s_waitcnt lgkmcnt(0)
	s_barrier
	s_setprio 1
	s_waitcnt lgkmcnt(0)
	v_mfma_f32_16x16x32_bf16 v[158:161], v[50:53], v[174:177], v[158:161]
	v_mfma_f32_16x16x32_bf16 v[154:157], v[58:61], v[174:177], v[154:157]
	v_mfma_f32_16x16x32_bf16 v[142:145], v[50:53], v[182:185], v[142:145]
	v_mfma_f32_16x16x32_bf16 v[138:141], v[58:61], v[182:185], v[138:141]
	v_mfma_f32_16x16x32_bf16 v[126:129], v[50:53], v[190:193], v[126:129]
	v_mfma_f32_16x16x32_bf16 v[122:125], v[58:61], v[190:193], v[122:125]
	v_mfma_f32_16x16x32_bf16 v[110:113], v[50:53], v[202:205], v[110:113]
	v_mfma_f32_16x16x32_bf16 v[106:109], v[58:61], v[202:205], v[106:109]
	v_mfma_f32_16x16x32_bf16 v[158:161], v[54:57], v[178:181], v[158:161]
	v_mfma_f32_16x16x32_bf16 v[154:157], v[62:65], v[178:181], v[154:157]
	v_mfma_f32_16x16x32_bf16 v[142:145], v[54:57], v[186:189], v[142:145]
	v_mfma_f32_16x16x32_bf16 v[138:141], v[62:65], v[186:189], v[138:141]
	v_mfma_f32_16x16x32_bf16 v[126:129], v[54:57], v[194:197], v[126:129]
	v_mfma_f32_16x16x32_bf16 v[122:125], v[62:65], v[194:197], v[122:125]
	v_mfma_f32_16x16x32_bf16 v[110:113], v[54:57], v[206:209], v[110:113]
	v_mfma_f32_16x16x32_bf16 v[106:109], v[62:65], v[206:209], v[106:109]
	s_setprio 0
	s_setprio 1
	v_mfma_f32_16x16x32_bf16 v[150:153], v[70:73], v[174:177], v[150:153]
	v_mfma_f32_16x16x32_bf16 v[146:149], v[82:85], v[174:177], v[146:149]
	v_mfma_f32_16x16x32_bf16 v[134:137], v[70:73], v[182:185], v[134:137]
	v_mfma_f32_16x16x32_bf16 v[130:133], v[82:85], v[182:185], v[130:133]
	v_mfma_f32_16x16x32_bf16 v[118:121], v[70:73], v[190:193], v[118:121]
	v_mfma_f32_16x16x32_bf16 v[114:117], v[82:85], v[190:193], v[114:117]
	v_mfma_f32_16x16x32_bf16 v[102:105], v[70:73], v[202:205], v[102:105]
	v_mfma_f32_16x16x32_bf16 v[98:101], v[82:85], v[202:205], v[98:101]
	v_mfma_f32_16x16x32_bf16 v[150:153], v[78:81], v[178:181], v[150:153]
	v_mfma_f32_16x16x32_bf16 v[146:149], v[86:89], v[178:181], v[146:149]
	v_mfma_f32_16x16x32_bf16 v[134:137], v[78:81], v[186:189], v[134:137]
	v_mfma_f32_16x16x32_bf16 v[130:133], v[86:89], v[186:189], v[130:133]
	v_mfma_f32_16x16x32_bf16 v[118:121], v[78:81], v[194:197], v[118:121]
	v_mfma_f32_16x16x32_bf16 v[114:117], v[86:89], v[194:197], v[114:117]
	v_mfma_f32_16x16x32_bf16 v[102:105], v[78:81], v[206:209], v[102:105]
	v_mfma_f32_16x16x32_bf16 v[98:101], v[86:89], v[206:209], v[98:101]
	s_setprio 0
	s_barrier
	s_add_i32 s53, s53, s59
	v_lshl_add_u64 v[198:199], s[28:29], 0, v[164:165]
	s_mov_b32 m0, s53
	ds_read_b128 v[174:177], v200 offset:16384
	ds_read_b128 v[178:181], v200 offset:17408
	ds_read_b128 v[182:185], v200 offset:18432
	ds_read_b128 v[186:189], v200 offset:19456
	ds_read_b128 v[190:193], v200 offset:20480
	ds_read_b128 v[194:197], v200 offset:21504
	ds_read_b128 v[202:205], v200 offset:22528
	ds_read_b128 v[206:209], v200 offset:23552
	global_load_lds_dwordx4 v[198:199], off
	s_add_i32 m0, s53, 0x2000
	s_add_u32 s54, s28, 0x80000
	v_lshl_add_u64 v[214:215], s[28:29], 0, v[168:169]
	s_addc_u32 s55, s29, 0
	s_add_i32 s53, s56, s59
	global_load_lds_dwordx4 v[214:215], off
	v_lshl_add_u64 v[210:211], s[54:55], 0, v[164:165]
	s_mov_b32 m0, s53
	v_lshl_add_u64 v[216:217], s[50:51], 0, v[162:163]
	global_load_lds_dwordx4 v[210:211], off
	v_lshl_add_u64 v[210:211], s[54:55], 0, v[168:169]
	s_add_i32 m0, s53, 0x2000
	v_lshl_add_u64 v[218:219], s[50:51], 0, v[166:167]
	global_load_lds_dwordx4 v[210:211], off
	s_mov_b32 m0, s60
	s_nop 0
	global_load_lds_dwordx4 v[216:217], off
	s_mov_b32 m0, s61
	s_nop 0
	global_load_lds_dwordx4 v[218:219], off
	s_waitcnt vmcnt(8)
	s_waitcnt lgkmcnt(0)
	s_barrier
; #define PG8_STAGE(bufoff, gbase, voff) do { _Pragma("unroll") for (int _i = 0; _i < 2; ++_i) \
;         __builtin_amdgcn_global_load_lds((const unsigned*)((const char*)(gbase) + (voff)[_i]), (LAS unsigned*)(lds + (bufoff) + ldsw + _i * 8192), 16, 0, 0); } while (0)
; #define PG8_LDA(dst, b, h) do { _Pragma("unroll") for (int m = 0; m < 4; ++m) _Pragma("unroll") for (int k = 0; k < 2; ++k) dst[m][k] = *(const LAS bf16x8*)(lds + PG8_SA(b, h) + aoff + m * 2048 + k * 1024); } while (0)
; #define PG8_LDB(dst, b, h) do { _Pragma("unroll") for (int n = 0; n < 2; ++n) _Pragma("unroll") for (int k = 0; k < 2; ++k) dst[n][k] = *(const LAS bf16x8*)(lds + PG8_SB(b, h) + boff + n * 2048 + k * 1024); } while (0)
; #define PG8_MMA(ai, bj, At, Bt) do { __builtin_amdgcn_s_setprio(1); _Pragma("unroll") for (int m = 0; m < 4; ++m) _Pragma("unroll") for (int n = 0; n < 2; ++n) _Pragma("unroll") for (int k = 0; k < 2; ++k) \
;         acc[ai][bj][m][n] = __builtin_amdgcn_mfma_f32_16x16x32_bf16(Bt[n][k], At[m][k], acc[ai][bj][m][n], 0, 0, 0); __builtin_amdgcn_s_setprio(0); } while (0)
; #define PG8_WAIT_V(n) asm volatile("s_waitcnt vmcnt(" #n ")" ::: "memory")
; #define PG8_WAIT_L(n) asm volatile("s_waitcnt lgkmcnt(" #n ")" ::: "memory")
; #define PG8_BAR __builtin_amdgcn_s_barrier()
; #define PG8_SCHED __builtin_amdgcn_sched_barrier(0)
; template <class Epi>
; __device__ __forceinline__ void gemm_phase(const int tid, LAS unsigned char* lds, const Gemm g, const StaticOrder& S, const Epi& E) {
;     ...
;             PG8_WAIT_V(8); PG8_WAIT_L(0); PG8_BAR; PG8_MMA(1, 0, At, B0); PG8_MMA(1, 1, At, B1); PG8_BAR; PG8_SCHED;
;             PG8_LDB(B0, 1, 0); PG8_LDB(B1, 1, 1); PG8_SCHED; PG8_LDA(At, 1, 0); PG8_STAGE(PG8_SA(0, 1), a2 + hstepA, voffA);
;             PG8_WAIT_V(8); PG8_WAIT_L(0); PG8_BAR; PG8_MMA(0, 0, At, B0); PG8_MMA(0, 1, At, B1); PG8_BAR; PG8_SCHED;
	s_setprio 1
	s_waitcnt lgkmcnt(0)
	v_mfma_f32_16x16x32_bf16 v[94:97], v[50:53], v[174:177], v[94:97]
	v_mfma_f32_16x16x32_bf16 v[90:93], v[58:61], v[174:177], v[90:93]
	v_mfma_f32_16x16x32_bf16 v[46:49], v[50:53], v[182:185], v[46:49]
	v_mfma_f32_16x16x32_bf16 v[42:45], v[58:61], v[182:185], v[42:45]
	v_mfma_f32_16x16x32_bf16 v[28:31], v[50:53], v[190:193], v[28:31]
	v_mfma_f32_16x16x32_bf16 v[24:27], v[58:61], v[190:193], v[24:27]
	v_mfma_f32_16x16x32_bf16 v[12:15], v[50:53], v[202:205], v[12:15]
	v_mfma_f32_16x16x32_bf16 v[8:11], v[58:61], v[202:205], v[8:11]
	v_mfma_f32_16x16x32_bf16 v[94:97], v[54:57], v[178:181], v[94:97]
	v_mfma_f32_16x16x32_bf16 v[90:93], v[62:65], v[178:181], v[90:93]
	v_mfma_f32_16x16x32_bf16 v[46:49], v[54:57], v[186:189], v[46:49]
	v_mfma_f32_16x16x32_bf16 v[42:45], v[62:65], v[186:189], v[42:45]
	v_mfma_f32_16x16x32_bf16 v[28:31], v[54:57], v[194:197], v[28:31]
	v_mfma_f32_16x16x32_bf16 v[24:27], v[62:65], v[194:197], v[24:27]
	v_mfma_f32_16x16x32_bf16 v[12:15], v[54:57], v[206:209], v[12:15]
	v_mfma_f32_16x16x32_bf16 v[8:11], v[62:65], v[206:209], v[8:11]
	s_setprio 0
	s_setprio 1
	v_mfma_f32_16x16x32_bf16 v[38:41], v[70:73], v[182:185], v[38:41]
	v_mfma_f32_16x16x32_bf16 v[34:37], v[82:85], v[182:185], v[34:37]
	v_mfma_f32_16x16x32_bf16 v[20:23], v[70:73], v[190:193], v[20:23]
	v_mfma_f32_16x16x32_bf16 v[16:19], v[82:85], v[190:193], v[16:19]
	v_mfma_f32_16x16x32_bf16 v[4:7], v[70:73], v[202:205], v[4:7]
	v_mfma_f32_16x16x32_bf16 v[0:3], v[82:85], v[202:205], v[0:3]
	v_mfma_f32_16x16x32_bf16 v[50:53], v[70:73], v[174:177], v[74:77]
	v_mfma_f32_16x16x32_bf16 v[54:57], v[82:85], v[174:177], v[66:69]
	v_mfma_f32_16x16x32_bf16 v[38:41], v[78:81], v[186:189], v[38:41]
	v_mfma_f32_16x16x32_bf16 v[34:37], v[86:89], v[186:189], v[34:37]
	v_mfma_f32_16x16x32_bf16 v[20:23], v[78:81], v[194:197], v[20:23]
	v_mfma_f32_16x16x32_bf16 v[16:19], v[86:89], v[194:197], v[16:19]
	v_mfma_f32_16x16x32_bf16 v[4:7], v[78:81], v[206:209], v[4:7]
	v_mfma_f32_16x16x32_bf16 v[0:3], v[86:89], v[206:209], v[0:3]
	v_mfma_f32_16x16x32_bf16 v[50:53], v[78:81], v[178:181], v[50:53]
	v_mfma_f32_16x16x32_bf16 v[54:57], v[86:89], v[178:181], v[54:57]
	s_setprio 0
	s_barrier
	s_add_i32 s53, 0, 0x18000
	s_add_i32 s54, 0, 0x1c000
	v_add_u32_e32 v70, s53, v33
	v_add_u32_e32 v74, s54, v33
	ds_read_b128 v[58:61], v70
	ds_read_b128 v[62:65], v70 offset:1024
	ds_read_b128 v[66:69], v70 offset:2048
	ds_read_b128 v[70:73], v70 offset:3072
	ds_read_b128 v[78:81], v74
	ds_read_b128 v[82:85], v74 offset:1024
	ds_read_b128 v[86:89], v74 offset:2048
	ds_read_b128 v[174:177], v74 offset:3072
	s_add_u32 s50, s50, 0x80000
	s_addc_u32 s51, s51, 0
	s_mov_b32 m0, s62
	v_lshl_add_u64 v[210:211], s[50:51], 0, v[162:163]
	ds_read_b128 v[74:77], v200 offset:32768
	ds_read_b128 v[178:181], v200 offset:33792
	ds_read_b128 v[182:185], v200 offset:34816
	ds_read_b128 v[186:189], v200 offset:35840
	ds_read_b128 v[190:193], v200 offset:36864
	ds_read_b128 v[194:197], v200 offset:37888
	ds_read_b128 v[202:205], v200 offset:38912
	ds_read_b128 v[206:209], v200 offset:39936
	global_load_lds_dwordx4 v[210:211], off
	v_lshl_add_u64 v[210:211], s[50:51], 0, v[166:167]
	s_mov_b32 m0, s63
	s_nop 0
	global_load_lds_dwordx4 v[210:211], off
	s_waitcnt vmcnt(8)
	s_waitcnt lgkmcnt(0)
	s_barrier
	s_setprio 1
	s_waitcnt lgkmcnt(0)
	v_mfma_f32_16x16x32_bf16 v[158:161], v[58:61], v[74:77], v[158:161]
	v_mfma_f32_16x16x32_bf16 v[154:157], v[66:69], v[74:77], v[154:157]
	v_mfma_f32_16x16x32_bf16 v[142:145], v[58:61], v[182:185], v[142:145]
	v_mfma_f32_16x16x32_bf16 v[138:141], v[66:69], v[182:185], v[138:141]
	v_mfma_f32_16x16x32_bf16 v[126:129], v[58:61], v[190:193], v[126:129]
	v_mfma_f32_16x16x32_bf16 v[122:125], v[66:69], v[190:193], v[122:125]
	v_mfma_f32_16x16x32_bf16 v[110:113], v[58:61], v[202:205], v[110:113]
	v_mfma_f32_16x16x32_bf16 v[106:109], v[66:69], v[202:205], v[106:109]
	v_mfma_f32_16x16x32_bf16 v[158:161], v[62:65], v[178:181], v[158:161]
	v_mfma_f32_16x16x32_bf16 v[154:157], v[70:73], v[178:181], v[154:157]
	v_mfma_f32_16x16x32_bf16 v[142:145], v[62:65], v[186:189], v[142:145]
	v_mfma_f32_16x16x32_bf16 v[138:141], v[70:73], v[186:189], v[138:141]
	v_mfma_f32_16x16x32_bf16 v[126:129], v[62:65], v[194:197], v[126:129]
	v_mfma_f32_16x16x32_bf16 v[122:125], v[70:73], v[194:197], v[122:125]
	v_mfma_f32_16x16x32_bf16 v[110:113], v[62:65], v[206:209], v[110:113]
	v_mfma_f32_16x16x32_bf16 v[106:109], v[70:73], v[206:209], v[106:109]
	s_setprio 0
	s_setprio 1
	v_mfma_f32_16x16x32_bf16 v[150:153], v[78:81], v[74:77], v[150:153]
	v_mfma_f32_16x16x32_bf16 v[146:149], v[86:89], v[74:77], v[146:149]
	v_mfma_f32_16x16x32_bf16 v[134:137], v[78:81], v[182:185], v[134:137]
	v_mfma_f32_16x16x32_bf16 v[130:133], v[86:89], v[182:185], v[130:133]
	v_mfma_f32_16x16x32_bf16 v[118:121], v[78:81], v[190:193], v[118:121]
	v_mfma_f32_16x16x32_bf16 v[114:117], v[86:89], v[190:193], v[114:117]
	v_mfma_f32_16x16x32_bf16 v[102:105], v[78:81], v[202:205], v[102:105]
	v_mfma_f32_16x16x32_bf16 v[98:101], v[86:89], v[202:205], v[98:101]
	v_mfma_f32_16x16x32_bf16 v[150:153], v[82:85], v[178:181], v[150:153]
	v_mfma_f32_16x16x32_bf16 v[146:149], v[174:177], v[178:181], v[146:149]
	v_mfma_f32_16x16x32_bf16 v[134:137], v[82:85], v[186:189], v[134:137]
	v_mfma_f32_16x16x32_bf16 v[130:133], v[174:177], v[186:189], v[130:133]
	v_mfma_f32_16x16x32_bf16 v[118:121], v[82:85], v[194:197], v[118:121]
	v_mfma_f32_16x16x32_bf16 v[114:117], v[174:177], v[194:197], v[114:117]
	v_mfma_f32_16x16x32_bf16 v[102:105], v[82:85], v[206:209], v[102:105]
	v_mfma_f32_16x16x32_bf16 v[98:101], v[174:177], v[206:209], v[98:101]
	s_setprio 0
	s_barrier
; #define PG8_STAGE(bufoff, gbase, voff) do { _Pragma("unroll") for (int _i = 0; _i < 2; ++_i) \
;         __builtin_amdgcn_global_load_lds((const unsigned*)((const char*)(gbase) + (voff)[_i]), (LAS unsigned*)(lds + (bufoff) + ldsw + _i * 8192), 16, 0, 0); } while (0)
; #define PG8_LDA(dst, b, h) do { _Pragma("unroll") for (int m = 0; m < 4; ++m) _Pragma("unroll") for (int k = 0; k < 2; ++k) dst[m][k] = *(const LAS bf16x8*)(lds + PG8_SA(b, h) + aoff + m * 2048 + k * 1024); } while (0)
; #define PG8_MMA(ai, bj, At, Bt) do { __builtin_amdgcn_s_setprio(1); _Pragma("unroll") for (int m = 0; m < 4; ++m) _Pragma("unroll") for (int n = 0; n < 2; ++n) _Pragma("unroll") for (int k = 0; k < 2; ++k) \
;         acc[ai][bj][m][n] = __builtin_amdgcn_mfma_f32_16x16x32_bf16(Bt[n][k], At[m][k], acc[ai][bj][m][n], 0, 0, 0); __builtin_amdgcn_s_setprio(0); } while (0)
; #define PG8_WAIT_V(n) asm volatile("s_waitcnt vmcnt(" #n ")" ::: "memory")
; #define PG8_WAIT_L(n) asm volatile("s_waitcnt lgkmcnt(" #n ")" ::: "memory")
; #define PG8_BAR __builtin_amdgcn_s_barrier()
; #define PG8_SCHED __builtin_amdgcn_sched_barrier(0)
; template <class Epi>
; __device__ __forceinline__ void gemm_phase(const int tid, LAS unsigned char* lds, const Gemm g, const StaticOrder& S, const Epi& E) {
;     ...
;         for (int t = 0; t < nt; t += 2) {
;     ...
;             PG8_LDA(At, 1, 1); PG8_STAGE(PG8_SB(1, 0), b3, voffB); PG8_STAGE(PG8_SB(1, 1), b3 + hstepB, voffB); PG8_STAGE(PG8_SA(1, 0), a3, voffA);
;             PG8_WAIT_V(8); PG8_WAIT_L(0); PG8_BAR; PG8_MMA(1, 0, At, B0); PG8_MMA(1, 1, At, B1); PG8_BAR; PG8_SCHED;
	s_add_i32 s50, s53, s59
	s_nop 2
	v_lshl_add_u64 v[74:75], v[198:199], 0, s[24:25]
	s_mov_b32 m0, s50
	ds_read_b128 v[178:181], v200 offset:49152
	ds_read_b128 v[182:185], v200 offset:50176
	ds_read_b128 v[186:189], v200 offset:51200
	ds_read_b128 v[190:193], v200 offset:52224
	ds_read_b128 v[194:197], v200 offset:53248
	ds_read_b128 v[202:205], v200 offset:54272
	ds_read_b128 v[206:209], v200 offset:55296
	ds_read_b128 v[210:213], v200 offset:56320
	global_load_lds_dwordx4 v[74:75], off
	s_add_i32 m0, s50, 0x2000
	s_add_u32 s28, s28, 0x80080
	v_lshl_add_u64 v[74:75], v[214:215], 0, s[24:25]
	s_addc_u32 s29, s29, 0
	s_add_i32 s50, s54, s59
	global_load_lds_dwordx4 v[74:75], off
	v_lshl_add_u64 v[74:75], s[28:29], 0, v[164:165]
	s_mov_b32 m0, s50
	s_nop 0
	global_load_lds_dwordx4 v[74:75], off
	v_lshl_add_u64 v[74:75], s[28:29], 0, v[168:169]
	s_add_i32 m0, s50, 0x2000
	s_nop 0
	global_load_lds_dwordx4 v[74:75], off
	v_lshl_add_u64 v[74:75], v[216:217], 0, s[24:25]
	s_mov_b32 m0, s68
	s_nop 0
	global_load_lds_dwordx4 v[74:75], off
	v_lshl_add_u64 v[74:75], v[218:219], 0, s[24:25]
	s_mov_b32 m0, s69
	s_nop 0
	global_load_lds_dwordx4 v[74:75], off
	s_waitcnt vmcnt(8)
	s_waitcnt lgkmcnt(0)
	s_barrier
	s_setprio 1
	s_waitcnt lgkmcnt(0)
	v_mfma_f32_16x16x32_bf16 v[94:97], v[58:61], v[178:181], v[94:97]
	v_mfma_f32_16x16x32_bf16 v[90:93], v[66:69], v[178:181], v[90:93]
	v_mfma_f32_16x16x32_bf16 v[46:49], v[58:61], v[186:189], v[46:49]
	v_mfma_f32_16x16x32_bf16 v[42:45], v[66:69], v[186:189], v[42:45]
	v_mfma_f32_16x16x32_bf16 v[28:31], v[58:61], v[194:197], v[28:31]
	v_mfma_f32_16x16x32_bf16 v[24:27], v[66:69], v[194:197], v[24:27]
	v_mfma_f32_16x16x32_bf16 v[12:15], v[58:61], v[206:209], v[12:15]
	v_mfma_f32_16x16x32_bf16 v[8:11], v[66:69], v[206:209], v[8:11]
	v_mfma_f32_16x16x32_bf16 v[94:97], v[62:65], v[182:185], v[94:97]
	v_mfma_f32_16x16x32_bf16 v[90:93], v[70:73], v[182:185], v[90:93]
	v_mfma_f32_16x16x32_bf16 v[46:49], v[62:65], v[190:193], v[46:49]
	v_mfma_f32_16x16x32_bf16 v[42:45], v[70:73], v[190:193], v[42:45]
	v_mfma_f32_16x16x32_bf16 v[28:31], v[62:65], v[202:205], v[28:31]
	v_mfma_f32_16x16x32_bf16 v[24:27], v[70:73], v[202:205], v[24:27]
	v_mfma_f32_16x16x32_bf16 v[12:15], v[62:65], v[210:213], v[12:15]
	v_mfma_f32_16x16x32_bf16 v[8:11], v[70:73], v[210:213], v[8:11]
	s_setprio 0
	s_setprio 1
	v_mfma_f32_16x16x32_bf16 v[50:53], v[78:81], v[178:181], v[50:53]
	v_mfma_f32_16x16x32_bf16 v[38:41], v[78:81], v[186:189], v[38:41]
	v_mfma_f32_16x16x32_bf16 v[34:37], v[86:89], v[186:189], v[34:37]
	v_mfma_f32_16x16x32_bf16 v[20:23], v[78:81], v[194:197], v[20:23]
	v_mfma_f32_16x16x32_bf16 v[16:19], v[86:89], v[194:197], v[16:19]
	v_mfma_f32_16x16x32_bf16 v[4:7], v[78:81], v[206:209], v[4:7]
	v_mfma_f32_16x16x32_bf16 v[0:3], v[86:89], v[206:209], v[0:3]
	v_mfma_f32_16x16x32_bf16 v[74:77], v[82:85], v[182:185], v[50:53]
	v_mfma_f32_16x16x32_bf16 v[50:53], v[86:89], v[178:181], v[54:57]
	v_mfma_f32_16x16x32_bf16 v[38:41], v[82:85], v[190:193], v[38:41]
	v_mfma_f32_16x16x32_bf16 v[34:37], v[174:177], v[190:193], v[34:37]
	v_mfma_f32_16x16x32_bf16 v[20:23], v[82:85], v[202:205], v[20:23]
	v_mfma_f32_16x16x32_bf16 v[16:19], v[174:177], v[202:205], v[16:19]
	v_mfma_f32_16x16x32_bf16 v[4:7], v[82:85], v[210:213], v[4:7]
	v_mfma_f32_16x16x32_bf16 v[0:3], v[174:177], v[210:213], v[0:3]
	v_mfma_f32_16x16x32_bf16 v[66:69], v[174:177], v[182:185], v[50:53]
	s_setprio 0
	s_barrier
	s_add_i32 s52, s52, 2
	s_add_u32 s0, s0, 0x100
	s_addc_u32 s1, s1, 0
	s_add_u32 s43, s43, 0x100
	s_addc_u32 s45, s45, 0
	s_cmp_gt_u32 s52, 29
	s_cbranch_scc0 .LBB0_5496
	s_and_b64 vcc, exec, s[30:31]
	s_cbranch_vccz .LBB0_5499
	s_barrier
